# peeled first K-loop iteration with zero-C MFMAs; per-tile accumulator zeroing removed
# baseline (speedup 1.0000x reference)
; __device__ __forceinline__ void gemm_phase(LAS unsigned char* lds, CParams& p, const Job& jb) {
;     ...
;     Unit cur, nxt; int ui = 0;
;     if (!S.next(0, cur)) return;
;     f32x4 acc[2][2][4][2];
; #pragma unroll
;     for (int a = 0; a < 2; ++a)
; #pragma unroll
;         for (int b = 0; b < 2; ++b)
; #pragma unroll
;             for (int m = 0; m < 4; ++m)
; #pragma unroll
;                 for (int n = 0; n < 2; ++n) acc[a][b][m][n] = (f32x4){0.f, 0.f, 0.f, 0.f};
;     bf16x8 At[4][2], B0[2][2], B1[2][2];
;     const char* cA = cur.A; const char* cB = cur.B;
;     ...
; #pragma unroll
;         for (int a = 0; a < 2; ++a)
; #pragma unroll
;             for (int b = 0; b < 2; ++b)
; #pragma unroll
;                 for (int m = 0; m < 4; ++m)
; #pragma unroll
;                     for (int n = 0; n < 2; ++n) acc[a][b][m][n] = (f32x4){0.f, 0.f, 0.f, 0.f};
;         cur = nxt; cA = nA; cB = nB; ++ui;
.LBB0_601:
	s_mov_b32 s3, s35
	s_mov_b32 s95, s34
	s_mov_b32 s92, s62
	s_mov_b32 s78, s96
	s_mov_b64 s[24:25], s[4:5]
	s_mov_b32 s30, s63
	s_andn2_b64 vcc, exec, s[6:7]
	s_mov_b64 s[10:11], s[86:87]
	s_cbranch_vccz .LBB0_913

; #define PG8_STAGE(bufoff, gbase, voff) do { _Pragma("unroll") for (int _i = 0; _i < 2; ++_i) \
;         __builtin_amdgcn_global_load_lds((const unsigned*)((const char*)(gbase) + (voff)[_i]), (LAS unsigned*)(lds + (bufoff) + ldsw + _i * 8192), 16, 0, 0); } while (0)
; #define PG8_LDA(dst, b, h) do { _Pragma("unroll") for (int m = 0; m < 4; ++m) _Pragma("unroll") for (int k = 0; k < 2; ++k) dst[m][k] = *(const LAS bf16x8*)(lds + PG8_SA(b, h) + aoff + m * 2048 + k * 1024); } while (0)
; #define PG8_LDB(dst, b, h) do { _Pragma("unroll") for (int n = 0; n < 2; ++n) _Pragma("unroll") for (int k = 0; k < 2; ++k) dst[n][k] = *(const LAS bf16x8*)(lds + PG8_SB(b, h) + boff + n * 2048 + k * 1024); } while (0)
; #define PG8_MMA(ai, bj, At, Bt) do { __builtin_amdgcn_s_setprio(1); _Pragma("unroll") for (int m = 0; m < 4; ++m) _Pragma("unroll") for (int n = 0; n < 2; ++n) _Pragma("unroll") for (int k = 0; k < 2; ++k) \
;         acc[ai][bj][m][n] = __builtin_amdgcn_mfma_f32_16x16x32_bf16(Bt[n][k], At[m][k], acc[ai][bj][m][n], 0, 0, 0); __builtin_amdgcn_s_setprio(0); } while (0)
; #define PG8_WAIT_L(n) asm volatile("s_waitcnt lgkmcnt(" #n ")" ::: "memory")
; #define PG8_BAR __builtin_amdgcn_s_barrier()
; #define PG8_SCHED __builtin_amdgcn_sched_barrier(0)
; __device__ __forceinline__ void gemm_phase(LAS unsigned char* lds, CParams& p, const Job& jb) {
;     ...
;         for (int t = 0; t < nt; t += 2) {
;             const bool last = (t == nt - 2);
;             const char* a1 = cA + (size_t)(t + 1) * kstep;
;             const char* a2 = last ? nA : cA + (size_t)(t + 2) * kstep; const char* b2 = last ? nB : cB + (size_t)(t + 2) * kstep;
;             const char* a3 = a2 + kstep; const char* b3 = b2 + kstep;
;             PG8_LDB(B0, 0, 0); PG8_SCHED; PG8_LDA(At, 0, 0); PG8_STAGE(PG8_SA(1, 1), a1 + hstepA, voffA);
;             PG8_WAIT_L(8); PG8_BAR; PG8_WAIT_L(0); PG8_MMA(0, 0, At, B0); PG8_BAR; PG8_SCHED;
;             PG8_LDB(B1, 0, 1); PG8_STAGE(PG8_SB(0, 0), b2, voffB);
;             PG8_BAR; PG8_WAIT_L(0); PG8_MMA(0, 1, At, B1); PG8_BAR;
;             PG8_LDA(At, 0, 1); PG8_STAGE(PG8_SA(0, 0), a2, voffA);
;             PG8_BAR; PG8_WAIT_L(0); PG8_MMA(1, 0, At, B0); PG8_BAR; PG8_SCHED;
;             PG8_STAGE(PG8_SB(0, 1), b2 + hstepB, voffB);
.LBB0_630:
	s_add_u32 s97, s10, 0x100
	s_addc_u32 s2, s11, 0
	s_add_u32 s10, s24, 0x80
	s_addc_u32 s11, s25, 0
	v_lshl_add_u64 v[128:129], s[10:11], 0, v[168:169]
	v_lshl_add_u64 v[130:131], s[10:11], 0, v[170:171]
	s_mov_b32 s1, 0
	s_mov_b64 s[10:11], 0
	s_add_i32 s1, s1, 2
	s_add_u32 s12, s24, s10
	s_addc_u32 s13, s25, s11
	s_add_u32 s12, s12, 0x100
	s_addc_u32 s13, s13, 0
	s_add_u32 s14, s97, s10
	s_addc_u32 s15, s2, s11
	s_add_i32 s16, 0, 0x10000
	v_add_u32_e32 v144, s16, v213
	ds_read_b128 v[132:135], v144
	ds_read_b128 v[136:139], v144 offset:1024
	ds_read_b128 v[140:143], v144 offset:2048
	ds_read_b128 v[144:147], v144 offset:3072
	s_cmp_eq_u32 s85, s10
	s_cselect_b32 s13, s5, s13
	s_cselect_b32 s12, s4, s12
	s_cselect_b32 s15, s87, s15
	s_cselect_b32 s14, s86, s14
	v_lshl_add_u64 v[216:217], v[128:129], 0, s[10:11]
	s_add_i32 m0, s65, 0xc000
	ds_read_b128 v[148:151], v214
	ds_read_b128 v[152:155], v214 offset:1024
	ds_read_b128 v[156:159], v214 offset:2048
	ds_read_b128 v[172:175], v214 offset:3072
	ds_read_b128 v[176:179], v214 offset:4096
	ds_read_b128 v[180:183], v214 offset:5120
	ds_read_b128 v[184:187], v214 offset:6144
	ds_read_b128 v[188:191], v214 offset:7168
	global_load_lds_dwordx4 v[216:217], off
	v_lshl_add_u64 v[216:217], v[130:131], 0, s[10:11]
	s_add_i32 m0, s65, 0xe000
	s_nop 0
	global_load_lds_dwordx4 v[216:217], off
	s_waitcnt lgkmcnt(8)
	s_barrier
	s_waitcnt lgkmcnt(0)
	s_waitcnt lgkmcnt(0)
	v_mfma_f32_16x16x32_bf16 v[124:127], v[132:135], v[148:151], 0
	v_mfma_f32_16x16x32_bf16 v[120:123], v[140:143], v[148:151], 0
	v_mfma_f32_16x16x32_bf16 v[116:119], v[132:135], v[156:159], 0
	v_mfma_f32_16x16x32_bf16 v[112:115], v[140:143], v[156:159], 0
	v_mfma_f32_16x16x32_bf16 v[108:111], v[132:135], v[176:179], 0
	v_mfma_f32_16x16x32_bf16 v[104:107], v[140:143], v[176:179], 0
	v_mfma_f32_16x16x32_bf16 v[100:103], v[132:135], v[184:187], 0
	v_mfma_f32_16x16x32_bf16 v[96:99], v[140:143], v[184:187], 0
	v_mfma_f32_16x16x32_bf16 v[124:127], v[136:139], v[152:155], v[124:127]
	v_mfma_f32_16x16x32_bf16 v[120:123], v[144:147], v[152:155], v[120:123]
	v_mfma_f32_16x16x32_bf16 v[116:119], v[136:139], v[172:175], v[116:119]
	v_mfma_f32_16x16x32_bf16 v[112:115], v[144:147], v[172:175], v[112:115]
	v_mfma_f32_16x16x32_bf16 v[108:111], v[136:139], v[180:183], v[108:111]
	v_mfma_f32_16x16x32_bf16 v[104:107], v[144:147], v[180:183], v[104:107]
	v_mfma_f32_16x16x32_bf16 v[100:103], v[136:139], v[188:191], v[100:103]
	v_mfma_f32_16x16x32_bf16 v[96:99], v[144:147], v[188:191], v[96:99]
	s_barrier
	s_add_i32 s17, 0, 0x14000
	s_add_i32 s16, s16, s64
	v_add_u32_e32 v215, s17, v213
	v_lshl_add_u64 v[232:233], s[14:15], 0, v[160:161]
	s_mov_b32 m0, s16
	ds_read_b128 v[216:219], v215
	ds_read_b128 v[220:223], v215 offset:1024
	ds_read_b128 v[224:227], v215 offset:2048
	ds_read_b128 v[228:231], v215 offset:3072
	global_load_lds_dwordx4 v[232:233], off
	v_lshl_add_u64 v[234:235], s[14:15], 0, v[166:167]
	s_add_i32 m0, s16, 0x2000
	s_nop 0
	global_load_lds_dwordx4 v[234:235], off
	s_barrier
	s_waitcnt lgkmcnt(0)
	s_waitcnt lgkmcnt(0)
	v_mfma_f32_16x16x32_bf16 v[92:95], v[216:219], v[148:151], 0
	v_mfma_f32_16x16x32_bf16 v[88:91], v[224:227], v[148:151], 0
	v_mfma_f32_16x16x32_bf16 v[84:87], v[216:219], v[156:159], 0
	v_mfma_f32_16x16x32_bf16 v[80:83], v[224:227], v[156:159], 0
	v_mfma_f32_16x16x32_bf16 v[76:79], v[216:219], v[176:179], 0
	v_mfma_f32_16x16x32_bf16 v[72:75], v[224:227], v[176:179], 0
	v_mfma_f32_16x16x32_bf16 v[68:71], v[216:219], v[184:187], 0
	v_mfma_f32_16x16x32_bf16 v[64:67], v[224:227], v[184:187], 0
	v_mfma_f32_16x16x32_bf16 v[92:95], v[220:223], v[152:155], v[92:95]
	v_mfma_f32_16x16x32_bf16 v[88:91], v[228:231], v[152:155], v[88:91]
	v_mfma_f32_16x16x32_bf16 v[84:87], v[220:223], v[172:175], v[84:87]
	v_mfma_f32_16x16x32_bf16 v[80:83], v[228:231], v[172:175], v[80:83]
	v_mfma_f32_16x16x32_bf16 v[76:79], v[220:223], v[180:183], v[76:79]
	v_mfma_f32_16x16x32_bf16 v[72:75], v[228:231], v[180:183], v[72:75]
	v_mfma_f32_16x16x32_bf16 v[68:71], v[220:223], v[188:191], v[68:71]
	v_mfma_f32_16x16x32_bf16 v[64:67], v[228:231], v[188:191], v[64:67]
	s_mov_b32 m0, s65
	v_lshl_add_u64 v[236:237], s[12:13], 0, v[162:163]
	s_barrier
	ds_read_b128 v[148:151], v214 offset:16384
	ds_read_b128 v[152:155], v214 offset:17408
	ds_read_b128 v[156:159], v214 offset:18432
	ds_read_b128 v[172:175], v214 offset:19456
	ds_read_b128 v[176:179], v214 offset:20480
	ds_read_b128 v[180:183], v214 offset:21504
	ds_read_b128 v[184:187], v214 offset:22528
	ds_read_b128 v[188:191], v214 offset:23552
	global_load_lds_dwordx4 v[236:237], off
	v_lshl_add_u64 v[238:239], s[12:13], 0, v[164:165]
	s_mov_b32 m0, s66
	s_nop 0
	global_load_lds_dwordx4 v[238:239], off
	s_barrier
	s_waitcnt lgkmcnt(0)
	s_waitcnt lgkmcnt(0)
	v_mfma_f32_16x16x32_bf16 v[60:63], v[132:135], v[148:151], 0
	v_mfma_f32_16x16x32_bf16 v[56:59], v[140:143], v[148:151], 0
	v_mfma_f32_16x16x32_bf16 v[52:55], v[132:135], v[156:159], 0
	v_mfma_f32_16x16x32_bf16 v[48:51], v[140:143], v[156:159], 0
	v_mfma_f32_16x16x32_bf16 v[44:47], v[132:135], v[176:179], 0
	v_mfma_f32_16x16x32_bf16 v[40:43], v[140:143], v[176:179], 0
	v_mfma_f32_16x16x32_bf16 v[36:39], v[132:135], v[184:187], 0
	v_mfma_f32_16x16x32_bf16 v[32:35], v[140:143], v[184:187], 0
	v_mfma_f32_16x16x32_bf16 v[60:63], v[136:139], v[152:155], v[60:63]
	v_mfma_f32_16x16x32_bf16 v[56:59], v[144:147], v[152:155], v[56:59]
	v_mfma_f32_16x16x32_bf16 v[52:55], v[136:139], v[172:175], v[52:55]
	v_mfma_f32_16x16x32_bf16 v[48:51], v[144:147], v[172:175], v[48:51]
	v_mfma_f32_16x16x32_bf16 v[44:47], v[136:139], v[180:183], v[44:47]
	v_mfma_f32_16x16x32_bf16 v[40:43], v[144:147], v[180:183], v[40:43]
	v_mfma_f32_16x16x32_bf16 v[36:39], v[136:139], v[188:191], v[36:39]
	v_mfma_f32_16x16x32_bf16 v[32:35], v[144:147], v[188:191], v[32:35]
	s_barrier
; #define PG8_STAGE(bufoff, gbase, voff) do { _Pragma("unroll") for (int _i = 0; _i < 2; ++_i) \
;         __builtin_amdgcn_global_load_lds((const unsigned*)((const char*)(gbase) + (voff)[_i]), (LAS unsigned*)(lds + (bufoff) + ldsw + _i * 8192), 16, 0, 0); } while (0)
; #define PG8_LDA(dst, b, h) do { _Pragma("unroll") for (int m = 0; m < 4; ++m) _Pragma("unroll") for (int k = 0; k < 2; ++k) dst[m][k] = *(const LAS bf16x8*)(lds + PG8_SA(b, h) + aoff + m * 2048 + k * 1024); } while (0)
; #define PG8_LDB(dst, b, h) do { _Pragma("unroll") for (int n = 0; n < 2; ++n) _Pragma("unroll") for (int k = 0; k < 2; ++k) dst[n][k] = *(const LAS bf16x8*)(lds + PG8_SB(b, h) + boff + n * 2048 + k * 1024); } while (0)
; #define PG8_MMA(ai, bj, At, Bt) do { __builtin_amdgcn_s_setprio(1); _Pragma("unroll") for (int m = 0; m < 4; ++m) _Pragma("unroll") for (int n = 0; n < 2; ++n) _Pragma("unroll") for (int k = 0; k < 2; ++k) \
;         acc[ai][bj][m][n] = __builtin_amdgcn_mfma_f32_16x16x32_bf16(Bt[n][k], At[m][k], acc[ai][bj][m][n], 0, 0, 0); __builtin_amdgcn_s_setprio(0); } while (0)
; #define PG8_WAIT_V(n) asm volatile("s_waitcnt vmcnt(" #n ")" ::: "memory")
; #define PG8_WAIT_L(n) asm volatile("s_waitcnt lgkmcnt(" #n ")" ::: "memory")
; #define PG8_BAR __builtin_amdgcn_s_barrier()
; #define PG8_SCHED __builtin_amdgcn_sched_barrier(0)
; __device__ __forceinline__ void gemm_phase(LAS unsigned char* lds, CParams& p, const Job& jb) {
;     ...
;             PG8_STAGE(PG8_SB(0, 1), b2 + hstepB, voffB);
;             PG8_WAIT_V(6); PG8_BAR; PG8_MMA(1, 1, At, B1); PG8_BAR;
;             PG8_LDB(B0, 1, 0); PG8_SCHED; PG8_LDA(At, 1, 0); PG8_STAGE(PG8_SA(0, 1), a2 + hstepA, voffA);
;             PG8_WAIT_L(8); PG8_BAR; PG8_WAIT_L(0); PG8_MMA(0, 0, At, B0); PG8_BAR; PG8_SCHED;
;             PG8_LDB(B1, 1, 1); PG8_STAGE(PG8_SB(1, 0), b3, voffB);
	s_add_u32 s14, s14, s76
	s_addc_u32 s15, s15, s77
	s_add_i32 s16, s17, s64
	v_lshl_add_u64 v[240:241], s[14:15], 0, v[160:161]
	s_mov_b32 m0, s16
	v_lshl_add_u64 v[242:243], s[14:15], 0, v[166:167]
	global_load_lds_dwordx4 v[240:241], off
	s_add_i32 m0, s16, 0x2000
	s_nop 0
	global_load_lds_dwordx4 v[242:243], off
	s_waitcnt vmcnt(6)
	s_barrier
	v_mfma_f32_16x16x32_bf16 v[28:31], v[216:219], v[148:151], 0
	v_mfma_f32_16x16x32_bf16 v[24:27], v[224:227], v[148:151], 0
	v_mfma_f32_16x16x32_bf16 v[20:23], v[216:219], v[156:159], 0
	v_mfma_f32_16x16x32_bf16 v[16:19], v[224:227], v[156:159], 0
	v_mfma_f32_16x16x32_bf16 v[12:15], v[216:219], v[176:179], 0
	v_mfma_f32_16x16x32_bf16 v[8:11], v[224:227], v[176:179], 0
	v_mfma_f32_16x16x32_bf16 v[4:7], v[216:219], v[184:187], 0
	v_mfma_f32_16x16x32_bf16 v[0:3], v[224:227], v[184:187], 0
	v_mfma_f32_16x16x32_bf16 v[28:31], v[220:223], v[152:155], v[28:31]
	v_mfma_f32_16x16x32_bf16 v[24:27], v[228:231], v[152:155], v[24:27]
	v_mfma_f32_16x16x32_bf16 v[20:23], v[220:223], v[172:175], v[20:23]
	v_mfma_f32_16x16x32_bf16 v[16:19], v[228:231], v[172:175], v[16:19]
	v_mfma_f32_16x16x32_bf16 v[12:15], v[220:223], v[180:183], v[12:15]
	v_mfma_f32_16x16x32_bf16 v[8:11], v[228:231], v[180:183], v[8:11]
	v_mfma_f32_16x16x32_bf16 v[4:7], v[220:223], v[188:191], v[4:7]
	v_mfma_f32_16x16x32_bf16 v[0:3], v[228:231], v[188:191], v[0:3]
	s_add_i32 s14, 0, 0x18000
	v_add_u32_e32 v144, s14, v213
	s_barrier
	ds_read_b128 v[132:135], v144
	ds_read_b128 v[136:139], v144 offset:1024
	ds_read_b128 v[140:143], v144 offset:2048
	ds_read_b128 v[144:147], v144 offset:3072
	s_add_u32 s12, s12, s74
	s_addc_u32 s13, s13, s75
	s_mov_b32 m0, s67
	v_lshl_add_u64 v[216:217], s[12:13], 0, v[162:163]
	ds_read_b128 v[148:151], v214 offset:32768
	ds_read_b128 v[152:155], v214 offset:33792
	ds_read_b128 v[156:159], v214 offset:34816
	ds_read_b128 v[172:175], v214 offset:35840
	ds_read_b128 v[176:179], v214 offset:36864
	ds_read_b128 v[180:183], v214 offset:37888
	ds_read_b128 v[184:187], v214 offset:38912
	ds_read_b128 v[188:191], v214 offset:39936
	global_load_lds_dwordx4 v[216:217], off
	v_lshl_add_u64 v[216:217], s[12:13], 0, v[164:165]
	s_mov_b32 m0, s94
	s_nop 0
	global_load_lds_dwordx4 v[216:217], off
	s_waitcnt lgkmcnt(8)
	s_barrier
	s_waitcnt lgkmcnt(0)
	s_waitcnt lgkmcnt(0)
	v_mfma_f32_16x16x32_bf16 v[124:127], v[132:135], v[148:151], v[124:127]
	v_mfma_f32_16x16x32_bf16 v[120:123], v[140:143], v[148:151], v[120:123]
	v_mfma_f32_16x16x32_bf16 v[116:119], v[132:135], v[156:159], v[116:119]
	v_mfma_f32_16x16x32_bf16 v[112:115], v[140:143], v[156:159], v[112:115]
	v_mfma_f32_16x16x32_bf16 v[108:111], v[132:135], v[176:179], v[108:111]
	v_mfma_f32_16x16x32_bf16 v[104:107], v[140:143], v[176:179], v[104:107]
	v_mfma_f32_16x16x32_bf16 v[100:103], v[132:135], v[184:187], v[100:103]
	v_mfma_f32_16x16x32_bf16 v[96:99], v[140:143], v[184:187], v[96:99]
	v_mfma_f32_16x16x32_bf16 v[124:127], v[136:139], v[152:155], v[124:127]
	v_mfma_f32_16x16x32_bf16 v[120:123], v[144:147], v[152:155], v[120:123]
	v_mfma_f32_16x16x32_bf16 v[116:119], v[136:139], v[172:175], v[116:119]
	v_mfma_f32_16x16x32_bf16 v[112:115], v[144:147], v[172:175], v[112:115]
	v_mfma_f32_16x16x32_bf16 v[108:111], v[136:139], v[180:183], v[108:111]
	v_mfma_f32_16x16x32_bf16 v[104:107], v[144:147], v[180:183], v[104:107]
	v_mfma_f32_16x16x32_bf16 v[100:103], v[136:139], v[188:191], v[100:103]
	v_mfma_f32_16x16x32_bf16 v[96:99], v[144:147], v[188:191], v[96:99]
	s_barrier
	s_add_i32 s12, 0, 0x1c000
	s_add_i32 s13, s14, s64
	v_add_u32_e32 v215, s12, v213
	v_lshl_add_u64 v[232:233], v[232:233], 0, s[90:91]
	s_mov_b32 m0, s13
	ds_read_b128 v[216:219], v215
	ds_read_b128 v[220:223], v215 offset:1024
	ds_read_b128 v[224:227], v215 offset:2048
	ds_read_b128 v[228:231], v215 offset:3072
	global_load_lds_dwordx4 v[232:233], off
	v_lshl_add_u64 v[232:233], v[234:235], 0, s[90:91]
	s_add_i32 m0, s13, 0x2000
	s_nop 0
	global_load_lds_dwordx4 v[232:233], off
	s_barrier
; #define PG8_STAGE(bufoff, gbase, voff) do { _Pragma("unroll") for (int _i = 0; _i < 2; ++_i) \
;         __builtin_amdgcn_global_load_lds((const unsigned*)((const char*)(gbase) + (voff)[_i]), (LAS unsigned*)(lds + (bufoff) + ldsw + _i * 8192), 16, 0, 0); } while (0)
; #define PG8_LDA(dst, b, h) do { _Pragma("unroll") for (int m = 0; m < 4; ++m) _Pragma("unroll") for (int k = 0; k < 2; ++k) dst[m][k] = *(const LAS bf16x8*)(lds + PG8_SA(b, h) + aoff + m * 2048 + k * 1024); } while (0)
; #define PG8_LDB(dst, b, h) do { _Pragma("unroll") for (int n = 0; n < 2; ++n) _Pragma("unroll") for (int k = 0; k < 2; ++k) dst[n][k] = *(const LAS bf16x8*)(lds + PG8_SB(b, h) + boff + n * 2048 + k * 1024); } while (0)
; #define PG8_MMA(ai, bj, At, Bt) do { __builtin_amdgcn_s_setprio(1); _Pragma("unroll") for (int m = 0; m < 4; ++m) _Pragma("unroll") for (int n = 0; n < 2; ++n) _Pragma("unroll") for (int k = 0; k < 2; ++k) \
;         acc[ai][bj][m][n] = __builtin_amdgcn_mfma_f32_16x16x32_bf16(Bt[n][k], At[m][k], acc[ai][bj][m][n], 0, 0, 0); __builtin_amdgcn_s_setprio(0); } while (0)
; #define PG8_WAIT_V(n) asm volatile("s_waitcnt vmcnt(" #n ")" ::: "memory")
; #define PG8_WAIT_L(n) asm volatile("s_waitcnt lgkmcnt(" #n ")" ::: "memory")
; #define PG8_BAR __builtin_amdgcn_s_barrier()
; #define PG8_SCHED __builtin_amdgcn_sched_barrier(0)
; __device__ __forceinline__ void gemm_phase(LAS unsigned char* lds, CParams& p, const Job& jb) {
;     ...
;             PG8_LDB(B1, 1, 1); PG8_STAGE(PG8_SB(1, 0), b3, voffB);
;             PG8_BAR; PG8_WAIT_L(0); PG8_MMA(0, 1, At, B1); PG8_BAR;
;             PG8_LDA(At, 1, 1); PG8_STAGE(PG8_SA(1, 0), a3, voffA);
;             PG8_BAR; PG8_WAIT_L(0); PG8_MMA(1, 0, At, B0); PG8_BAR; PG8_SCHED;
;             PG8_STAGE(PG8_SB(1, 1), b3 + hstepB, voffB);
;             PG8_WAIT_V(6); PG8_BAR; PG8_MMA(1, 1, At, B1); PG8_BAR;
	s_waitcnt lgkmcnt(0)
	s_waitcnt lgkmcnt(0)
	v_mfma_f32_16x16x32_bf16 v[92:95], v[216:219], v[148:151], v[92:95]
	v_mfma_f32_16x16x32_bf16 v[88:91], v[224:227], v[148:151], v[88:91]
	v_mfma_f32_16x16x32_bf16 v[84:87], v[216:219], v[156:159], v[84:87]
	v_mfma_f32_16x16x32_bf16 v[80:83], v[224:227], v[156:159], v[80:83]
	v_mfma_f32_16x16x32_bf16 v[76:79], v[216:219], v[176:179], v[76:79]
	v_mfma_f32_16x16x32_bf16 v[72:75], v[224:227], v[176:179], v[72:75]
	v_mfma_f32_16x16x32_bf16 v[68:71], v[216:219], v[184:187], v[68:71]
	v_mfma_f32_16x16x32_bf16 v[64:67], v[224:227], v[184:187], v[64:67]
	v_mfma_f32_16x16x32_bf16 v[92:95], v[220:223], v[152:155], v[92:95]
	v_mfma_f32_16x16x32_bf16 v[88:91], v[228:231], v[152:155], v[88:91]
	v_mfma_f32_16x16x32_bf16 v[84:87], v[220:223], v[172:175], v[84:87]
	v_mfma_f32_16x16x32_bf16 v[80:83], v[228:231], v[172:175], v[80:83]
	v_mfma_f32_16x16x32_bf16 v[76:79], v[220:223], v[180:183], v[76:79]
	v_mfma_f32_16x16x32_bf16 v[72:75], v[228:231], v[180:183], v[72:75]
	v_mfma_f32_16x16x32_bf16 v[68:71], v[220:223], v[188:191], v[68:71]
	v_mfma_f32_16x16x32_bf16 v[64:67], v[228:231], v[188:191], v[64:67]
	s_mov_b32 m0, s33
	v_lshl_add_u64 v[232:233], v[236:237], 0, s[90:91]
	s_barrier
	ds_read_b128 v[148:151], v214 offset:49152
	ds_read_b128 v[152:155], v214 offset:50176
	ds_read_b128 v[156:159], v214 offset:51200
	ds_read_b128 v[172:175], v214 offset:52224
	ds_read_b128 v[176:179], v214 offset:53248
	ds_read_b128 v[180:183], v214 offset:54272
	ds_read_b128 v[184:187], v214 offset:55296
	ds_read_b128 v[188:191], v214 offset:56320
	global_load_lds_dwordx4 v[232:233], off
	v_lshl_add_u64 v[232:233], v[238:239], 0, s[90:91]
	s_mov_b32 m0, s60
	s_nop 0
	global_load_lds_dwordx4 v[232:233], off
	s_barrier
	s_waitcnt lgkmcnt(0)
	s_waitcnt lgkmcnt(0)
	v_mfma_f32_16x16x32_bf16 v[60:63], v[132:135], v[148:151], v[60:63]
	v_mfma_f32_16x16x32_bf16 v[56:59], v[140:143], v[148:151], v[56:59]
	v_mfma_f32_16x16x32_bf16 v[52:55], v[132:135], v[156:159], v[52:55]
	v_mfma_f32_16x16x32_bf16 v[48:51], v[140:143], v[156:159], v[48:51]
	v_mfma_f32_16x16x32_bf16 v[44:47], v[132:135], v[176:179], v[44:47]
	v_mfma_f32_16x16x32_bf16 v[40:43], v[140:143], v[176:179], v[40:43]
	v_mfma_f32_16x16x32_bf16 v[36:39], v[132:135], v[184:187], v[36:39]
	v_mfma_f32_16x16x32_bf16 v[32:35], v[140:143], v[184:187], v[32:35]
	v_mfma_f32_16x16x32_bf16 v[60:63], v[136:139], v[152:155], v[60:63]
	v_mfma_f32_16x16x32_bf16 v[56:59], v[144:147], v[152:155], v[56:59]
	v_mfma_f32_16x16x32_bf16 v[52:55], v[136:139], v[172:175], v[52:55]
	v_mfma_f32_16x16x32_bf16 v[48:51], v[144:147], v[172:175], v[48:51]
	v_mfma_f32_16x16x32_bf16 v[44:47], v[136:139], v[180:183], v[44:47]
	v_mfma_f32_16x16x32_bf16 v[40:43], v[144:147], v[180:183], v[40:43]
	v_mfma_f32_16x16x32_bf16 v[36:39], v[136:139], v[188:191], v[36:39]
	v_mfma_f32_16x16x32_bf16 v[32:35], v[144:147], v[188:191], v[32:35]
	s_barrier
	s_add_i32 s12, s12, s64
	v_lshl_add_u64 v[132:133], v[240:241], 0, s[90:91]
	s_mov_b32 m0, s12
	s_nop 0
	global_load_lds_dwordx4 v[132:133], off
	v_lshl_add_u64 v[132:133], v[242:243], 0, s[90:91]
	s_add_i32 m0, s12, 0x2000
	s_nop 0
	global_load_lds_dwordx4 v[132:133], off
	s_waitcnt vmcnt(6)
	s_barrier
	v_mfma_f32_16x16x32_bf16 v[28:31], v[216:219], v[148:151], v[28:31]
	v_mfma_f32_16x16x32_bf16 v[24:27], v[224:227], v[148:151], v[24:27]
	v_mfma_f32_16x16x32_bf16 v[20:23], v[216:219], v[156:159], v[20:23]
	v_mfma_f32_16x16x32_bf16 v[16:19], v[224:227], v[156:159], v[16:19]
	v_mfma_f32_16x16x32_bf16 v[12:15], v[216:219], v[176:179], v[12:15]
	v_mfma_f32_16x16x32_bf16 v[8:11], v[224:227], v[176:179], v[8:11]
	v_mfma_f32_16x16x32_bf16 v[4:7], v[216:219], v[184:187], v[4:7]
	v_mfma_f32_16x16x32_bf16 v[0:3], v[224:227], v[184:187], v[0:3]
	v_mfma_f32_16x16x32_bf16 v[28:31], v[220:223], v[152:155], v[28:31]
	v_mfma_f32_16x16x32_bf16 v[24:27], v[228:231], v[152:155], v[24:27]
	v_mfma_f32_16x16x32_bf16 v[20:23], v[220:223], v[172:175], v[20:23]
	v_mfma_f32_16x16x32_bf16 v[16:19], v[228:231], v[172:175], v[16:19]
	v_mfma_f32_16x16x32_bf16 v[12:15], v[220:223], v[180:183], v[12:15]
	v_mfma_f32_16x16x32_bf16 v[8:11], v[228:231], v[180:183], v[8:11]
	v_mfma_f32_16x16x32_bf16 v[4:7], v[220:223], v[188:191], v[4:7]
	v_mfma_f32_16x16x32_bf16 v[0:3], v[228:231], v[188:191], v[0:3]
	s_add_u32 s10, s10, 0x100
	s_addc_u32 s11, s11, 0
	s_cmp_ge_u32 s1, s84
	s_barrier
	s_cbranch_scc1 .Lkl_done

; #define FOR_ROWS _Pragma("unroll") for (int ai = 0; ai < 2; ++ai) _Pragma("unroll") for (int m = 0; m < 4; ++m)
; __device__ __forceinline__ void epilogue(const int kind, CParams& p, const f32x4 (&acc)[2][2][4][2], const Unit& u, const int wr, const int wc, const int fr_in, const int fq_in) {
;     ...
;     case E_DOWN_HALF: {
;         FOR_ROWS { ROWDEF
; #pragma unroll
;             for (int bj = 0; bj < 2; ++bj) { float* hp = p.out + row * 1024 + u.pn * 256 + bj * 128 + cw;
; #pragma unroll
;                 for (int j = 0; j < 4; ++j) { unsafeAtomicAdd(hp + j, acc[ai][bj][m][0][j]); unsafeAtomicAdd(hp + 4 + j, acc[ai][bj][m][1][j]); } } }
;     } break;
.Lkl_done:
	v_mov_b32_e32 v215, v211
	v_mov_b32_e32 v216, v212
	s_cmp_eq_u32 s3, 13
	s_cbranch_scc1 .Lmy_down
	s_cmp_eq_u32 s3, 12
	s_cbranch_scc1 .Lmy_ffn1
	s_cmp_lt_i32 s3, 7
	v_lshl_add_u32 v172, v216, 3, s31
	s_mov_b64 s[10:11], -1
	s_cbranch_scc1 .LBB0_849
	s_cmp_lt_i32 s3, 11
	s_cbranch_scc1 .LBB0_639
	s_cmp_gt_i32 s3, 12
	s_cbranch_scc0 .LBB0_640
	s_cmp_gt_i32 s3, 13
	s_mov_b64 s[26:27], -1
	s_cbranch_scc0 .LBB0_641
	s_cmp_eq_u32 s3, 14
	s_cbranch_scc0 .LBB0_638
	v_add_u32_e32 v128, s0, v215
	s_ashr_i32 s79, s78, 31
	v_ashrrev_i32_e32 v129, 31, v128
	v_lshl_add_u64 v[130:131], v[128:129], 0, s[78:79]
	s_lshl_b32 s10, s92, 8
	v_lshlrev_b64 v[130:131], 12, v[130:131]
	s_ashr_i32 s11, s10, 31
	v_ashrrev_i32_e32 v173, 31, v172
	v_lshl_add_u64 v[130:131], s[82:83], 0, v[130:131]
	s_lshl_b64 s[10:11], s[10:11], 2
	v_lshl_add_u64 v[130:131], v[130:131], 0, s[10:11]
	v_lshlrev_b64 v[132:133], 2, v[172:173]
	v_lshl_add_u64 v[130:131], v[130:131], 0, v[132:133]
	global_atomic_add_f32 v[130:131], v124, off
	global_atomic_add_f32 v[130:131], v120, off offset:16
	global_atomic_add_f32 v[130:131], v125, off offset:4
	global_atomic_add_f32 v[130:131], v121, off offset:20
	global_atomic_add_f32 v[130:131], v126, off offset:8
	global_atomic_add_f32 v[130:131], v122, off offset:24
	global_atomic_add_f32 v[130:131], v127, off offset:12
	global_atomic_add_f32 v[130:131], v123, off offset:28
	global_atomic_add_f32 v[130:131], v92, off offset:512
	global_atomic_add_f32 v[130:131], v88, off offset:528
	global_atomic_add_f32 v[130:131], v93, off offset:516
	global_atomic_add_f32 v[130:131], v89, off offset:532
	global_atomic_add_f32 v[130:131], v94, off offset:520
	global_atomic_add_f32 v[130:131], v90, off offset:536
	global_atomic_add_f32 v[130:131], v95, off offset:524
	global_atomic_add_f32 v[130:131], v91, off offset:540
	v_add_u32_e32 v130, 16, v128
	v_ashrrev_i32_e32 v131, 31, v130
	v_lshl_add_u64 v[130:131], v[130:131], 0, s[78:79]
	v_lshlrev_b64 v[130:131], 12, v[130:131]
	v_lshl_add_u64 v[130:131], s[82:83], 0, v[130:131]
	v_lshl_add_u64 v[130:131], v[130:131], 0, s[10:11]
	v_lshl_add_u64 v[130:131], v[130:131], 0, v[132:133]
	global_atomic_add_f32 v[130:131], v116, off
	global_atomic_add_f32 v[130:131], v112, off offset:16
	global_atomic_add_f32 v[130:131], v117, off offset:4
	global_atomic_add_f32 v[130:131], v113, off offset:20
	global_atomic_add_f32 v[130:131], v118, off offset:8
	global_atomic_add_f32 v[130:131], v114, off offset:24
	global_atomic_add_f32 v[130:131], v119, off offset:12
	global_atomic_add_f32 v[130:131], v115, off offset:28
	global_atomic_add_f32 v[130:131], v84, off offset:512
	global_atomic_add_f32 v[130:131], v80, off offset:528
	global_atomic_add_f32 v[130:131], v85, off offset:516
	global_atomic_add_f32 v[130:131], v81, off offset:532
	global_atomic_add_f32 v[130:131], v86, off offset:520
	global_atomic_add_f32 v[130:131], v82, off offset:536
	global_atomic_add_f32 v[130:131], v87, off offset:524
	global_atomic_add_f32 v[130:131], v83, off offset:540
	v_add_u32_e32 v130, 32, v128
	v_ashrrev_i32_e32 v131, 31, v130
	v_lshl_add_u64 v[130:131], v[130:131], 0, s[78:79]
	v_lshlrev_b64 v[130:131], 12, v[130:131]
	v_lshl_add_u64 v[130:131], s[82:83], 0, v[130:131]
	v_lshl_add_u64 v[130:131], v[130:131], 0, s[10:11]
	v_lshl_add_u64 v[130:131], v[130:131], 0, v[132:133]
	global_atomic_add_f32 v[130:131], v108, off
	global_atomic_add_f32 v[130:131], v104, off offset:16
	global_atomic_add_f32 v[130:131], v109, off offset:4
	global_atomic_add_f32 v[130:131], v105, off offset:20
	global_atomic_add_f32 v[130:131], v110, off offset:8
	global_atomic_add_f32 v[130:131], v106, off offset:24
	global_atomic_add_f32 v[130:131], v111, off offset:12
	global_atomic_add_f32 v[130:131], v107, off offset:28
	global_atomic_add_f32 v[130:131], v76, off offset:512
	global_atomic_add_f32 v[130:131], v72, off offset:528
	global_atomic_add_f32 v[130:131], v77, off offset:516
	global_atomic_add_f32 v[130:131], v73, off offset:532
	global_atomic_add_f32 v[130:131], v78, off offset:520
	global_atomic_add_f32 v[130:131], v74, off offset:536
	global_atomic_add_f32 v[130:131], v79, off offset:524
	global_atomic_add_f32 v[130:131], v75, off offset:540
	v_add_u32_e32 v130, 48, v128
	v_ashrrev_i32_e32 v131, 31, v130
	v_lshl_add_u64 v[130:131], v[130:131], 0, s[78:79]
	v_lshlrev_b64 v[130:131], 12, v[130:131]
	v_lshl_add_u64 v[130:131], s[82:83], 0, v[130:131]
	v_lshl_add_u64 v[130:131], v[130:131], 0, s[10:11]
	v_lshl_add_u64 v[130:131], v[130:131], 0, v[132:133]
	global_atomic_add_f32 v[130:131], v100, off
	global_atomic_add_f32 v[130:131], v96, off offset:16
	global_atomic_add_f32 v[130:131], v101, off offset:4
	global_atomic_add_f32 v[130:131], v97, off offset:20
	global_atomic_add_f32 v[130:131], v102, off offset:8
	global_atomic_add_f32 v[130:131], v98, off offset:24
	global_atomic_add_f32 v[130:131], v103, off offset:12
	global_atomic_add_f32 v[130:131], v99, off offset:28
	global_atomic_add_f32 v[130:131], v68, off offset:512
	global_atomic_add_f32 v[130:131], v64, off offset:528
; #define FOR_ROWS _Pragma("unroll") for (int ai = 0; ai < 2; ++ai) _Pragma("unroll") for (int m = 0; m < 4; ++m)
; __device__ __forceinline__ void epilogue(const int kind, CParams& p, const f32x4 (&acc)[2][2][4][2], const Unit& u, const int wr, const int wc, const int fr_in, const int fq_in) {
;     ...
;     case E_DOWN_HALF: {
;         FOR_ROWS { ROWDEF
; #pragma unroll
;             for (int bj = 0; bj < 2; ++bj) { float* hp = p.out + row * 1024 + u.pn * 256 + bj * 128 + cw;
; #pragma unroll
;                 for (int j = 0; j < 4; ++j) { unsafeAtomicAdd(hp + j, acc[ai][bj][m][0][j]); unsafeAtomicAdd(hp + 4 + j, acc[ai][bj][m][1][j]); } } }
;     } break;
	global_atomic_add_f32 v[130:131], v69, off offset:516
	global_atomic_add_f32 v[130:131], v65, off offset:532
	global_atomic_add_f32 v[130:131], v70, off offset:520
	global_atomic_add_f32 v[130:131], v66, off offset:536
	global_atomic_add_f32 v[130:131], v71, off offset:524
	global_atomic_add_f32 v[130:131], v67, off offset:540
	v_add_u32_e32 v130, 0x80, v128
	v_ashrrev_i32_e32 v131, 31, v130
	v_lshl_add_u64 v[130:131], v[130:131], 0, s[78:79]
	v_lshlrev_b64 v[130:131], 12, v[130:131]
	v_lshl_add_u64 v[130:131], s[82:83], 0, v[130:131]
	v_lshl_add_u64 v[130:131], v[130:131], 0, s[10:11]
	v_lshl_add_u64 v[130:131], v[130:131], 0, v[132:133]
	global_atomic_add_f32 v[130:131], v60, off
	global_atomic_add_f32 v[130:131], v56, off offset:16
	global_atomic_add_f32 v[130:131], v61, off offset:4
	global_atomic_add_f32 v[130:131], v57, off offset:20
	global_atomic_add_f32 v[130:131], v62, off offset:8
	global_atomic_add_f32 v[130:131], v58, off offset:24
	global_atomic_add_f32 v[130:131], v63, off offset:12
	global_atomic_add_f32 v[130:131], v59, off offset:28
	global_atomic_add_f32 v[130:131], v28, off offset:512
	global_atomic_add_f32 v[130:131], v24, off offset:528
	global_atomic_add_f32 v[130:131], v29, off offset:516
	global_atomic_add_f32 v[130:131], v25, off offset:532
	global_atomic_add_f32 v[130:131], v30, off offset:520
	global_atomic_add_f32 v[130:131], v26, off offset:536
	global_atomic_add_f32 v[130:131], v31, off offset:524
	global_atomic_add_f32 v[130:131], v27, off offset:540
	v_add_u32_e32 v130, 0x90, v128
	v_ashrrev_i32_e32 v131, 31, v130
	v_lshl_add_u64 v[130:131], v[130:131], 0, s[78:79]
	v_lshlrev_b64 v[130:131], 12, v[130:131]
	v_lshl_add_u64 v[130:131], s[82:83], 0, v[130:131]
	v_lshl_add_u64 v[130:131], v[130:131], 0, s[10:11]
	v_lshl_add_u64 v[130:131], v[130:131], 0, v[132:133]
	global_atomic_add_f32 v[130:131], v52, off
	global_atomic_add_f32 v[130:131], v48, off offset:16
	global_atomic_add_f32 v[130:131], v53, off offset:4
	global_atomic_add_f32 v[130:131], v49, off offset:20
	global_atomic_add_f32 v[130:131], v54, off offset:8
	global_atomic_add_f32 v[130:131], v50, off offset:24
	global_atomic_add_f32 v[130:131], v55, off offset:12
	global_atomic_add_f32 v[130:131], v51, off offset:28
	global_atomic_add_f32 v[130:131], v20, off offset:512
	global_atomic_add_f32 v[130:131], v16, off offset:528
	global_atomic_add_f32 v[130:131], v21, off offset:516
	global_atomic_add_f32 v[130:131], v17, off offset:532
	global_atomic_add_f32 v[130:131], v22, off offset:520
	global_atomic_add_f32 v[130:131], v18, off offset:536
	global_atomic_add_f32 v[130:131], v23, off offset:524
	global_atomic_add_f32 v[130:131], v19, off offset:540
	v_add_u32_e32 v130, 0xa0, v128
	v_ashrrev_i32_e32 v131, 31, v130
	v_add_u32_e32 v128, 0xb0, v128
	v_lshl_add_u64 v[130:131], v[130:131], 0, s[78:79]
	v_ashrrev_i32_e32 v129, 31, v128
	v_lshlrev_b64 v[130:131], 12, v[130:131]
	v_lshl_add_u64 v[128:129], v[128:129], 0, s[78:79]
	v_lshl_add_u64 v[130:131], s[82:83], 0, v[130:131]
	v_lshlrev_b64 v[128:129], 12, v[128:129]
	v_lshl_add_u64 v[130:131], v[130:131], 0, s[10:11]
	v_lshl_add_u64 v[128:129], s[82:83], 0, v[128:129]
	v_lshl_add_u64 v[130:131], v[130:131], 0, v[132:133]
	v_lshl_add_u64 v[128:129], v[128:129], 0, s[10:11]
	global_atomic_add_f32 v[130:131], v44, off
	global_atomic_add_f32 v[130:131], v40, off offset:16
	global_atomic_add_f32 v[130:131], v45, off offset:4
	global_atomic_add_f32 v[130:131], v41, off offset:20
	global_atomic_add_f32 v[130:131], v46, off offset:8
	global_atomic_add_f32 v[130:131], v42, off offset:24
	global_atomic_add_f32 v[130:131], v47, off offset:12
	global_atomic_add_f32 v[130:131], v43, off offset:28
	global_atomic_add_f32 v[130:131], v12, off offset:512
	global_atomic_add_f32 v[130:131], v8, off offset:528
	global_atomic_add_f32 v[130:131], v13, off offset:516
	global_atomic_add_f32 v[130:131], v9, off offset:532
	global_atomic_add_f32 v[130:131], v14, off offset:520
	global_atomic_add_f32 v[130:131], v10, off offset:536
	global_atomic_add_f32 v[130:131], v15, off offset:524
	global_atomic_add_f32 v[130:131], v11, off offset:540
	v_lshl_add_u64 v[128:129], v[128:129], 0, v[132:133]
	global_atomic_add_f32 v[128:129], v36, off
	global_atomic_add_f32 v[128:129], v32, off offset:16
	global_atomic_add_f32 v[128:129], v37, off offset:4
	global_atomic_add_f32 v[128:129], v33, off offset:20
	global_atomic_add_f32 v[128:129], v38, off offset:8
	global_atomic_add_f32 v[128:129], v34, off offset:24
	global_atomic_add_f32 v[128:129], v39, off offset:12
	global_atomic_add_f32 v[128:129], v35, off offset:28
	global_atomic_add_f32 v[128:129], v4, off offset:512
	global_atomic_add_f32 v[128:129], v0, off offset:528
	global_atomic_add_f32 v[128:129], v5, off offset:516
	global_atomic_add_f32 v[128:129], v1, off offset:532
	global_atomic_add_f32 v[128:129], v6, off offset:520
	global_atomic_add_f32 v[128:129], v2, off offset:536
	global_atomic_add_f32 v[128:129], v7, off offset:524
	global_atomic_add_f32 v[128:129], v3, off offset:540
